# SB attention loop unrolled x2 with alternating K/V register sets, loads issued 2 blocks ahead, no per-block vmcnt(0) copy
# speedup vs baseline: 1.0032x; 1.0032x over previous
.LBB0_422:
	s_ashr_i32 s89, s87, 7
	s_bfe_u32 s63, s87, 0x40003
	v_mbcnt_lo_u32_b32 v4, -1, 0
	v_mbcnt_hi_u32_b32 v4, -1, v4
	s_lshl_b32 s88, s89, 11
	v_and_b32_e32 v5, 31, v4
	s_mul_i32 s89, s89, 20
	v_or_b32_e32 v0, s88, v5
	s_add_i32 s0, s89, s63
	v_ashrrev_i32_e32 v1, 31, v0
	s_add_i32 s0, s0, 4
	v_ashrrev_i32_e32 v6, 5, v4
	v_lshlrev_b64 v[0:1], 12, v[0:1]
	s_ashr_i32 s1, s0, 31
	v_lshl_add_u64 v[0:1], s[48:49], 0, v[0:1]
	s_lshl_b32 s33, s63, 6
	s_lshl_b32 s56, s63, 7
	v_lshlrev_b32_e32 v2, 3, v6
	s_lshl_b64 s[0:1], s[0:1], 18
	v_lshl_add_u64 v[0:1], v[0:1], 0, s[56:57]
	s_waitcnt lgkmcnt(0)
	v_ashrrev_i32_e32 v3, 31, v2
	s_add_u32 s4, s52, s0
	s_waitcnt vmcnt(11)
	v_lshl_add_u64 v[128:129], v[2:3], 1, v[0:1]
	s_addc_u32 s5, s53, s1
	v_lshl_add_u64 v[0:1], v[128:129], 0, s[64:65]
	s_add_u32 s0, s58, s0
	global_load_dwordx4 v[48:51], v[0:1], off offset:2048
	global_load_dwordx4 v[52:55], v[0:1], off offset:2080
	global_load_dwordx4 v[56:59], v[0:1], off offset:2112
	global_load_dwordx4 v[60:63], v[0:1], off offset:2144
	s_addc_u32 s1, s59, s1
	v_lshlrev_b32_e32 v0, 3, v4
	s_add_u32 s6, s4, s60
	v_ashrrev_i32_e32 v1, 31, v0
	s_addc_u32 s7, s5, 0
	v_lshlrev_b64 v[0:1], 1, v[0:1]
	v_lshl_add_u64 v[2:3], s[6:7], 0, v[0:1]
	v_lshl_add_u64 v[130:131], s[0:1], 0, v[0:1]
	global_load_dwordx4 v[64:67], v[2:3], off
	global_load_dwordx4 v[68:71], v[2:3], off offset:1024
	global_load_dwordx4 v[72:75], v[2:3], off offset:2048
	global_load_dwordx4 v[80:83], v[2:3], off offset:3072
	v_lshl_add_u64 v[2:3], v[130:131], 0, s[60:61]
	global_load_dwordx4 v[76:79], v[2:3], off
	global_load_dwordx4 v[84:87], v[2:3], off offset:1024
	global_load_dwordx4 v[88:91], v[2:3], off offset:2048
	global_load_dwordx4 v[92:95], v[2:3], off offset:3072
	s_waitcnt vmcnt(22)
	v_lshl_add_u64 v[132:133], s[4:5], 0, v[0:1]
	s_max_i32 s98, s43, 1
	s_add_i32 s98, s98, -1
	s_lshl_b32 s98, s98, 12
	s_mov_b32 s99, 0
	v_lshl_add_u64 v[196:197], v[132:133], 0, s[98:99]
	global_load_dwordx4 v[96:99], v[196:197], off
	global_load_dwordx4 v[100:103], v[196:197], off offset:1024
	global_load_dwordx4 v[104:107], v[196:197], off offset:2048
	global_load_dwordx4 v[108:111], v[196:197], off offset:3072
	v_lshl_add_u64 v[196:197], v[130:131], 0, s[98:99]
	global_load_dwordx4 v[112:115], v[196:197], off
	global_load_dwordx4 v[116:119], v[196:197], off offset:1024
	global_load_dwordx4 v[120:123], v[196:197], off offset:2048
	global_load_dwordx4 v[124:127], v[196:197], off offset:3072
	v_lshlrev_b32_e32 v0, 4, v4
	v_and_b32_e32 v8, 0xfffffe00, v0
	v_ashrrev_i32_e32 v0, 3, v4
	v_and_b32_e32 v1, 7, v4
	v_add_u32_e32 v2, 8, v0
	v_lshlrev_b32_e32 v160, 4, v1
	v_cmp_eq_u32_e64 s[6:7], 0, v1
	v_ashrrev_i32_e32 v1, 31, v0
	v_ashrrev_i32_e32 v3, 31, v2
	v_lshlrev_b32_e32 v9, 7, v0
	v_lshlrev_b64 v[134:135], 12, v[0:1]
	s_waitcnt vmcnt(21)
	v_lshlrev_b32_e32 v136, 1, v0
	v_lshlrev_b32_e32 v10, 7, v2
	v_lshlrev_b64 v[138:139], 12, v[2:3]
	s_waitcnt vmcnt(20)
	v_lshlrev_b32_e32 v140, 1, v2
	v_add_u32_e32 v2, 16, v0
	v_add_u32_e32 v0, 24, v0
	v_lshlrev_b32_e32 v6, 2, v6
	v_ashrrev_i32_e32 v3, 31, v2
	v_ashrrev_i32_e32 v1, 31, v0
	v_lshlrev_b32_e32 v11, 7, v2
	v_lshlrev_b64 v[142:143], 12, v[2:3]
	s_waitcnt vmcnt(19)
	v_lshlrev_b32_e32 v144, 1, v2
	v_lshlrev_b32_e32 v2, 7, v0
	v_lshlrev_b64 v[146:147], 12, v[0:1]
	s_waitcnt vmcnt(18)
	v_lshlrev_b32_e32 v148, 1, v0
	v_or_b32_e32 v0, 1, v6
	v_cmp_lt_i32_e64 s[10:11], v0, v5
	v_or_b32_e32 v0, 2, v6
	v_cmp_lt_i32_e64 s[12:13], v0, v5
	v_or_b32_e32 v0, 3, v6
	v_cmp_lt_i32_e64 s[14:15], v0, v5
	v_add_u32_e32 v0, 8, v6
	v_cmp_lt_i32_e64 s[16:17], v0, v5
	v_add_u32_e32 v0, 9, v6
	v_cmp_lt_i32_e64 s[18:19], v0, v5
	v_add_u32_e32 v0, 10, v6
	v_cmp_lt_i32_e64 s[20:21], v0, v5
	v_add_u32_e32 v0, 11, v6
	v_cmp_lt_i32_e64 s[22:23], v0, v5
	v_add_u32_e32 v0, 16, v6
	v_cmp_lt_i32_e64 s[24:25], v0, v5
	v_add_u32_e32 v0, 17, v6
	v_cmp_lt_i32_e64 s[26:27], v0, v5
	v_add_u32_e32 v0, 18, v6
	v_cmp_lt_i32_e64 s[28:29], v0, v5
	v_add_u32_e32 v0, 19, v6
	v_cmp_lt_i32_e64 s[30:31], v0, v5
	v_add_u32_e32 v0, 24, v6
	v_cmp_lt_i32_e64 s[34:35], v0, v5
	v_add_u32_e32 v0, 25, v6
	v_cmp_lt_i32_e64 s[36:37], v0, v5
	v_add_u32_e32 v0, 26, v6
	s_add_u32 s94, s84, s56
	v_cmp_gt_u32_e64 s[4:5], 32, v4
	v_lshl_add_u32 v7, v5, 1, s3
	v_add_u32_e32 v4, s3, v160
	v_cmp_lt_i32_e64 s[38:39], v0, v5
	v_add_u32_e32 v0, 27, v6
	s_addc_u32 s95, s85, 0
	v_ashrrev_i32_e32 v137, 31, v136
	v_ashrrev_i32_e32 v141, 31, v140
	v_ashrrev_i32_e32 v145, 31, v144
	v_ashrrev_i32_e32 v149, 31, v148
	v_cmp_lt_i32_e64 s[8:9], v6, v5
	v_cmp_lt_i32_e64 s[40:41], v0, v5
	v_lshl_add_u64 v[150:151], s[94:95], 0, v[160:161]
	v_add_u32_e32 v160, v7, v8
	v_add_u32_e32 v172, v4, v9
	v_add_u32_e32 v173, v4, v10
	v_add_u32_e32 v174, v4, v11
	v_add_u32_e32 v175, v4, v2
	s_mov_b32 s42, s57
	s_branch .LBB0_424

.Lsb_a:
	s_max_i32 s98, s90, 2
	s_add_i32 s98, s98, -2
	s_lshl_b32 s98, s98, 12
	s_cmp_lg_u32 s90, s92
	s_waitcnt vmcnt(12)
	v_mfma_f32_32x32x16_bf16 v[32:47], v[64:67], v[48:51], 0
	v_mfma_f32_32x32x16_bf16 v[32:47], v[68:71], v[52:55], v[32:47]
	v_mfma_f32_32x32x16_bf16 v[32:47], v[72:75], v[56:59], v[32:47]
	v_mfma_f32_32x32x16_bf16 v[32:47], v[80:83], v[60:63], v[32:47]
	v_lshl_add_u64 v[196:197], v[132:133], 0, s[98:99]
	global_load_dwordx4 v[64:67], v[196:197], off
	global_load_dwordx4 v[68:71], v[196:197], off offset:1024
	global_load_dwordx4 v[72:75], v[196:197], off offset:2048
	global_load_dwordx4 v[80:83], v[196:197], off offset:3072
	s_nop 7
	v_max_f32_e32 v33, v33, v33
	v_min_f32_e32 v33, 0x42fc0000, v33
	v_exp_f32_e32 v163, v33
	v_max_f32_e32 v32, v32, v32
	v_min_f32_e32 v32, 0x42fc0000, v32
	v_exp_f32_e32 v162, v32
	v_max_f32_e32 v32, v34, v34
	v_add_f32_e32 v34, 1.0, v163
	v_min_f32_e32 v32, 0x42fc0000, v32
	v_exp_f32_e32 v164, v32
	v_max_f32_e32 v32, v35, v35
	v_rcp_f32_e32 v155, v34
	v_max_f32_e32 v34, v36, v36
	v_max_f32_e32 v35, v38, v38
	v_min_f32_e32 v34, 0x42fc0000, v34
	v_min_f32_e32 v35, 0x42fc0000, v35
	v_max_f32_e32 v36, v40, v40
	v_max_f32_e32 v38, v44, v44
	v_exp_f32_e32 v176, v34
	v_max_f32_e32 v34, v37, v37
	v_exp_f32_e32 v178, v35
	v_max_f32_e32 v35, v39, v39
	v_min_f32_e32 v36, 0x42fc0000, v36
	v_max_f32_e32 v37, v42, v42
	v_min_f32_e32 v38, 0x42fc0000, v38
	v_max_f32_e32 v39, v46, v46
	v_exp_f32_e32 v40, v36
	v_max_f32_e32 v36, v41, v41
	v_min_f32_e32 v37, 0x42fc0000, v37
	v_exp_f32_e32 v44, v38
	v_max_f32_e32 v38, v45, v45
	v_min_f32_e32 v39, 0x42fc0000, v39
	v_min_f32_e32 v34, 0x42fc0000, v34
	v_min_f32_e32 v36, 0x42fc0000, v36
	v_exp_f32_e32 v180, v37
	v_max_f32_e32 v37, v43, v43
	v_min_f32_e32 v38, 0x42fc0000, v38
	v_exp_f32_e32 v182, v39
	v_max_f32_e32 v39, v47, v47
	v_min_f32_e32 v32, 0x42fc0000, v32
	v_exp_f32_e32 v177, v34
	v_min_f32_e32 v35, 0x42fc0000, v35
	v_exp_f32_e32 v41, v36
	v_min_f32_e32 v37, 0x42fc0000, v37
	v_exp_f32_e32 v45, v38
	v_min_f32_e32 v39, 0x42fc0000, v39
	v_exp_f32_e32 v165, v32
	v_exp_f32_e32 v179, v35
	v_exp_f32_e32 v181, v37
	v_exp_f32_e32 v183, v39
	v_add_f32_e32 v34, 1.0, v176
	v_add_f32_e32 v36, 1.0, v40
	v_add_f32_e32 v38, 1.0, v44
	v_add_f32_e32 v33, 1.0, v162
	v_rcp_f32_e32 v156, v34
	v_add_f32_e32 v34, 1.0, v177
	v_rcp_f32_e32 v158, v36
	v_add_f32_e32 v36, 1.0, v41
	v_rcp_f32_e32 v170, v38
	v_add_f32_e32 v38, 1.0, v45
	v_rcp_f32_e32 v154, v33
	v_add_f32_e32 v32, 1.0, v164
	v_add_f32_e32 v33, 1.0, v165
	v_rcp_f32_e32 v157, v34
	v_add_f32_e32 v34, 1.0, v178
	v_add_f32_e32 v35, 1.0, v179
	v_rcp_f32_e32 v159, v36
	v_add_f32_e32 v36, 1.0, v180
	v_add_f32_e32 v37, 1.0, v181
	v_rcp_f32_e32 v171, v38
	v_add_f32_e32 v38, 1.0, v182
	v_add_f32_e32 v39, 1.0, v183
	v_rcp_f32_e32 v32, v32
	v_rcp_f32_e32 v33, v33
	v_rcp_f32_e32 v34, v34
	v_rcp_f32_e32 v35, v35
	v_rcp_f32_e32 v36, v36
	v_rcp_f32_e32 v37, v37
	v_rcp_f32_e32 v38, v38
	v_rcp_f32_e32 v39, v39
	v_pk_mul_f32 v[166:167], v[162:163], v[154:155]
	v_pk_mul_f32 v[168:169], v[164:165], v[32:33]
	v_pk_mul_f32 v[162:163], v[176:177], v[156:157]
	v_pk_mul_f32 v[164:165], v[178:179], v[34:35]
	v_pk_mul_f32 v[42:43], v[40:41], v[158:159]
	v_pk_mul_f32 v[46:47], v[180:181], v[36:37]
	v_pk_mul_f32 v[40:41], v[44:45], v[170:171]
	v_pk_mul_f32 v[44:45], v[182:183], v[38:39]
	s_cbranch_scc1 .Lsb_a_nomask
	s_or_b64 vcc, s[40:41], s[38:39]
	v_cndmask_b32_e32 v44, 0, v44, vcc
	s_or_b64 vcc, vcc, s[36:37]
	v_cndmask_b32_e32 v41, 0, v41, vcc
	s_or_b64 vcc, vcc, s[34:35]
	v_cndmask_b32_e32 v40, 0, v40, vcc
	s_or_b64 vcc, vcc, s[30:31]
	v_cndmask_b32_e32 v47, 0, v47, vcc
	s_or_b64 vcc, vcc, s[28:29]
	v_cndmask_b32_e32 v46, 0, v46, vcc
	s_or_b64 vcc, vcc, s[26:27]
	v_cndmask_b32_e32 v43, 0, v43, vcc
	s_or_b64 vcc, vcc, s[24:25]
	v_cndmask_b32_e32 v42, 0, v42, vcc
	s_or_b64 vcc, vcc, s[22:23]
	v_cndmask_b32_e32 v165, 0, v165, vcc
	s_or_b64 vcc, vcc, s[20:21]
	v_cndmask_b32_e32 v164, 0, v164, vcc
	s_or_b64 vcc, vcc, s[18:19]
	v_cndmask_b32_e32 v163, 0, v163, vcc
	s_or_b64 vcc, vcc, s[16:17]
	v_cndmask_b32_e32 v162, 0, v162, vcc
	s_or_b64 vcc, vcc, s[14:15]
	v_cndmask_b32_e32 v169, 0, v169, vcc
	s_or_b64 vcc, vcc, s[12:13]
	v_cndmask_b32_e32 v168, 0, v168, vcc
	s_or_b64 vcc, vcc, s[10:11]
	v_cndmask_b32_e32 v167, 0, v167, vcc
	s_or_b64 vcc, vcc, s[8:9]
	v_cndmask_b32_e64 v154, 1.0, v154, s[8:9]
	v_cndmask_b32_e64 v155, 1.0, v155, s[10:11]
	v_cndmask_b32_e64 v32, 1.0, v32, s[12:13]
	v_cndmask_b32_e64 v33, 1.0, v33, s[14:15]
	v_cndmask_b32_e64 v156, 1.0, v156, s[16:17]
	v_cndmask_b32_e64 v157, 1.0, v157, s[18:19]
	v_cndmask_b32_e64 v34, 1.0, v34, s[20:21]
	v_cndmask_b32_e64 v35, 1.0, v35, s[22:23]
	v_cndmask_b32_e64 v158, 1.0, v158, s[24:25]
	v_cndmask_b32_e64 v159, 1.0, v159, s[26:27]
	v_cndmask_b32_e64 v36, 1.0, v36, s[28:29]
	v_cndmask_b32_e64 v37, 1.0, v37, s[30:31]
	v_cndmask_b32_e64 v170, 1.0, v170, s[34:35]
	v_cndmask_b32_e64 v171, 1.0, v171, s[36:37]
	v_cndmask_b32_e64 v38, 1.0, v38, s[38:39]
	v_cndmask_b32_e64 v39, 1.0, v39, s[40:41]
	v_cndmask_b32_e64 v45, 0, v45, s[40:41]
	v_cndmask_b32_e32 v166, 0, v166, vcc
.Lsb_a_nomask:
	v_mul_f32_e32 v38, v38, v39
	v_mul_f32_e32 v32, v32, v33
	v_mul_f32_e32 v36, v36, v37
	v_mul_f32_e32 v180, v171, v38
	v_mul_f32_e32 v176, v155, v32
	v_mul_f32_e32 v179, v159, v36
	v_mul_f32_e32 v155, v170, v180
	v_mul_f32_e32 v34, v34, v35
	v_mul_f32_e32 v152, v158, v179
	v_mov_b32_e32 v182, v155
	v_mul_f32_e32 v178, v157, v34
	v_mov_b32_e32 v158, v152
	v_permlane32_swap_b32_e32 v155, v182
	v_mul_f32_e32 v177, v154, v176
	v_mul_f32_e32 v154, v156, v178
	v_permlane32_swap_b32_e32 v152, v158
	v_mul_f32_e32 v159, v155, v182
	v_mov_b32_e32 v156, v154
	v_pk_mul_f32 v[170:171], v[152:153], v[158:159]
	s_nop 0
	v_permlane32_swap_b32_e32 v154, v156
	v_mov_b32_e32 v155, v170
	v_mov_b32_e32 v157, v171
	v_mov_b32_e32 v181, v177
	v_pk_mul_f32 v[154:155], v[154:155], v[156:157]
	s_nop 0
	v_permlane32_swap_b32_e32 v177, v181
	v_mul_f32_e32 v152, v154, v155
	v_mul_f32_e32 v154, v152, v181
	v_mul_f32_e32 v156, v155, v156
	v_cndmask_b32_e64 v154, v152, v154, s[4:5]
	v_cndmask_b32_e64 v155, v155, v156, s[4:5]
	v_mul_f32_e32 v33, v33, v154
	v_mul_f32_e32 v32, v32, v154
	v_mul_f32_e32 v35, v35, v155
	v_mul_f32_e32 v34, v34, v155
	v_mul_f32_e32 v157, v169, v154
	v_mul_f32_e32 v33, v168, v33
	v_mul_f32_e32 v32, v167, v32
	v_mul_f32_e32 v154, v176, v154
	v_mul_f32_e32 v156, v165, v155
	v_mul_f32_e32 v35, v164, v35
	v_mul_f32_e32 v34, v163, v34
	v_mul_f32_e32 v155, v178, v155
	v_mul_f32_e32 v154, v166, v154
	v_mul_f32_e32 v155, v162, v155
	v_mul_f32_e32 v158, v171, v158
	v_cvt_pk_bf16_f32 v32, v154, v32
	v_cvt_pk_bf16_f32 v33, v33, v157
	v_cvt_pk_bf16_f32 v34, v155, v34
	v_cvt_pk_bf16_f32 v35, v35, v156
	v_cndmask_b32_e64 v158, v171, v158, s[4:5]
	s_waitcnt vmcnt(12)
	v_mfma_f32_32x32x16_bf16 v[16:31], v[32:35], v[76:79], v[16:31]
	v_mul_f32_e32 v36, v36, v158
	v_mul_f32_e32 v36, v43, v36
	v_mul_f32_e32 v43, v179, v158
	v_mul_f32_e32 v42, v42, v43
	v_mul_f32_e32 v43, v153, v182
	v_cndmask_b32_e64 v43, v153, v43, s[4:5]
	v_mul_f32_e32 v38, v38, v43
	v_mfma_f32_32x32x16_bf16 v[0:15], v[32:35], v[84:87], v[0:15]
	v_mul_f32_e32 v32, v180, v43
	v_mul_f32_e32 v37, v37, v158
	v_mul_f32_e32 v39, v39, v43
	v_mul_f32_e32 v34, v41, v38
	v_mul_f32_e32 v35, v40, v32
	v_mul_f32_e32 v47, v47, v158
	v_mul_f32_e32 v37, v46, v37
	v_mul_f32_e32 v45, v45, v43
	v_mul_f32_e32 v39, v44, v39
	v_cvt_pk_bf16_f32 v32, v42, v36
	v_cvt_pk_bf16_f32 v33, v37, v47
	v_cvt_pk_bf16_f32 v34, v35, v34
	v_cvt_pk_bf16_f32 v35, v39, v45
	v_mul_f32_e32 v36, v177, v181
	s_nop 0
	v_mfma_f32_32x32x16_bf16 v[16:31], v[32:35], v[88:91], v[16:31]
	v_mul_f32_e32 v153, v36, v152
	v_mfma_f32_32x32x16_bf16 v[0:15], v[32:35], v[92:95], v[0:15]
	v_lshl_add_u64 v[196:197], v[130:131], 0, s[98:99]
	global_load_dwordx4 v[76:79], v[196:197], off
	global_load_dwordx4 v[84:87], v[196:197], off offset:1024
	global_load_dwordx4 v[88:91], v[196:197], off offset:2048
	global_load_dwordx4 v[92:95], v[196:197], off offset:3072
	s_cmp_eq_u32 s90, 0
	s_cbranch_scc1 .LBB0_433
	s_mov_b32 s56, 0x800000
	v_cmp_gt_f32_e32 vcc, s56, v153
	s_cmp_eq_u64 vcc, exec
	s_cbranch_scc1 .LBB0_433
	s_add_i32 s90, s90, -1
.Lsb_b:
	s_max_i32 s98, s90, 2
	s_add_i32 s98, s98, -2
	s_lshl_b32 s98, s98, 12
	s_cmp_lg_u32 s90, s92
	s_waitcnt vmcnt(12)
	v_mfma_f32_32x32x16_bf16 v[32:47], v[96:99], v[48:51], 0
	v_mfma_f32_32x32x16_bf16 v[32:47], v[100:103], v[52:55], v[32:47]
	v_mfma_f32_32x32x16_bf16 v[32:47], v[104:107], v[56:59], v[32:47]
	v_mfma_f32_32x32x16_bf16 v[32:47], v[108:111], v[60:63], v[32:47]
	v_lshl_add_u64 v[196:197], v[132:133], 0, s[98:99]
	global_load_dwordx4 v[96:99], v[196:197], off
	global_load_dwordx4 v[100:103], v[196:197], off offset:1024
	global_load_dwordx4 v[104:107], v[196:197], off offset:2048
	global_load_dwordx4 v[108:111], v[196:197], off offset:3072
	s_nop 7
	v_max_f32_e32 v33, v33, v33
	v_min_f32_e32 v33, 0x42fc0000, v33
	v_exp_f32_e32 v163, v33
	v_max_f32_e32 v32, v32, v32
	v_min_f32_e32 v32, 0x42fc0000, v32
	v_exp_f32_e32 v162, v32
	v_max_f32_e32 v32, v34, v34
	v_add_f32_e32 v34, 1.0, v163
	v_min_f32_e32 v32, 0x42fc0000, v32
	v_exp_f32_e32 v164, v32
	v_max_f32_e32 v32, v35, v35
	v_rcp_f32_e32 v155, v34
	v_max_f32_e32 v34, v36, v36
	v_max_f32_e32 v35, v38, v38
	v_min_f32_e32 v34, 0x42fc0000, v34
	v_min_f32_e32 v35, 0x42fc0000, v35
	v_max_f32_e32 v36, v40, v40
	v_max_f32_e32 v38, v44, v44
	v_exp_f32_e32 v176, v34
	v_max_f32_e32 v34, v37, v37
	v_exp_f32_e32 v178, v35
	v_max_f32_e32 v35, v39, v39
	v_min_f32_e32 v36, 0x42fc0000, v36
	v_max_f32_e32 v37, v42, v42
	v_min_f32_e32 v38, 0x42fc0000, v38
	v_max_f32_e32 v39, v46, v46
	v_exp_f32_e32 v40, v36
	v_max_f32_e32 v36, v41, v41
	v_min_f32_e32 v37, 0x42fc0000, v37
	v_exp_f32_e32 v44, v38
	v_max_f32_e32 v38, v45, v45
	v_min_f32_e32 v39, 0x42fc0000, v39
	v_min_f32_e32 v34, 0x42fc0000, v34
	v_min_f32_e32 v36, 0x42fc0000, v36
	v_exp_f32_e32 v180, v37
	v_max_f32_e32 v37, v43, v43
	v_min_f32_e32 v38, 0x42fc0000, v38
	v_exp_f32_e32 v182, v39
	v_max_f32_e32 v39, v47, v47
	v_min_f32_e32 v32, 0x42fc0000, v32
	v_exp_f32_e32 v177, v34
	v_min_f32_e32 v35, 0x42fc0000, v35
	v_exp_f32_e32 v41, v36
	v_min_f32_e32 v37, 0x42fc0000, v37
	v_exp_f32_e32 v45, v38
	v_min_f32_e32 v39, 0x42fc0000, v39
	v_exp_f32_e32 v165, v32
	v_exp_f32_e32 v179, v35
	v_exp_f32_e32 v181, v37
	v_exp_f32_e32 v183, v39
	v_add_f32_e32 v34, 1.0, v176
	v_add_f32_e32 v36, 1.0, v40
	v_add_f32_e32 v38, 1.0, v44
	v_add_f32_e32 v33, 1.0, v162
	v_rcp_f32_e32 v156, v34
	v_add_f32_e32 v34, 1.0, v177
	v_rcp_f32_e32 v158, v36
	v_add_f32_e32 v36, 1.0, v41
	v_rcp_f32_e32 v170, v38
	v_add_f32_e32 v38, 1.0, v45
	v_rcp_f32_e32 v154, v33
	v_add_f32_e32 v32, 1.0, v164
	v_add_f32_e32 v33, 1.0, v165
	v_rcp_f32_e32 v157, v34
	v_add_f32_e32 v34, 1.0, v178
	v_add_f32_e32 v35, 1.0, v179
	v_rcp_f32_e32 v159, v36
	v_add_f32_e32 v36, 1.0, v180
	v_add_f32_e32 v37, 1.0, v181
	v_rcp_f32_e32 v171, v38
	v_add_f32_e32 v38, 1.0, v182
	v_add_f32_e32 v39, 1.0, v183
	v_rcp_f32_e32 v32, v32
	v_rcp_f32_e32 v33, v33
	v_rcp_f32_e32 v34, v34
	v_rcp_f32_e32 v35, v35
	v_rcp_f32_e32 v36, v36
	v_rcp_f32_e32 v37, v37
	v_rcp_f32_e32 v38, v38
	v_rcp_f32_e32 v39, v39
	v_pk_mul_f32 v[166:167], v[162:163], v[154:155]
	v_pk_mul_f32 v[168:169], v[164:165], v[32:33]
	v_pk_mul_f32 v[162:163], v[176:177], v[156:157]
	v_pk_mul_f32 v[164:165], v[178:179], v[34:35]
	v_pk_mul_f32 v[42:43], v[40:41], v[158:159]
	v_pk_mul_f32 v[46:47], v[180:181], v[36:37]
	v_pk_mul_f32 v[40:41], v[44:45], v[170:171]
	v_pk_mul_f32 v[44:45], v[182:183], v[38:39]
	s_cbranch_scc1 .Lsb_b_nomask
	s_or_b64 vcc, s[40:41], s[38:39]
	v_cndmask_b32_e32 v44, 0, v44, vcc
	s_or_b64 vcc, vcc, s[36:37]
	v_cndmask_b32_e32 v41, 0, v41, vcc
	s_or_b64 vcc, vcc, s[34:35]
	v_cndmask_b32_e32 v40, 0, v40, vcc
	s_or_b64 vcc, vcc, s[30:31]
	v_cndmask_b32_e32 v47, 0, v47, vcc
	s_or_b64 vcc, vcc, s[28:29]
	v_cndmask_b32_e32 v46, 0, v46, vcc
	s_or_b64 vcc, vcc, s[26:27]
	v_cndmask_b32_e32 v43, 0, v43, vcc
	s_or_b64 vcc, vcc, s[24:25]
	v_cndmask_b32_e32 v42, 0, v42, vcc
	s_or_b64 vcc, vcc, s[22:23]
	v_cndmask_b32_e32 v165, 0, v165, vcc
	s_or_b64 vcc, vcc, s[20:21]
	v_cndmask_b32_e32 v164, 0, v164, vcc
	s_or_b64 vcc, vcc, s[18:19]
	v_cndmask_b32_e32 v163, 0, v163, vcc
	s_or_b64 vcc, vcc, s[16:17]
	v_cndmask_b32_e32 v162, 0, v162, vcc
	s_or_b64 vcc, vcc, s[14:15]
	v_cndmask_b32_e32 v169, 0, v169, vcc
	s_or_b64 vcc, vcc, s[12:13]
	v_cndmask_b32_e32 v168, 0, v168, vcc
	s_or_b64 vcc, vcc, s[10:11]
	v_cndmask_b32_e32 v167, 0, v167, vcc
	s_or_b64 vcc, vcc, s[8:9]
	v_cndmask_b32_e64 v154, 1.0, v154, s[8:9]
	v_cndmask_b32_e64 v155, 1.0, v155, s[10:11]
	v_cndmask_b32_e64 v32, 1.0, v32, s[12:13]
	v_cndmask_b32_e64 v33, 1.0, v33, s[14:15]
	v_cndmask_b32_e64 v156, 1.0, v156, s[16:17]
	v_cndmask_b32_e64 v157, 1.0, v157, s[18:19]
	v_cndmask_b32_e64 v34, 1.0, v34, s[20:21]
	v_cndmask_b32_e64 v35, 1.0, v35, s[22:23]
	v_cndmask_b32_e64 v158, 1.0, v158, s[24:25]
	v_cndmask_b32_e64 v159, 1.0, v159, s[26:27]
	v_cndmask_b32_e64 v36, 1.0, v36, s[28:29]
	v_cndmask_b32_e64 v37, 1.0, v37, s[30:31]
	v_cndmask_b32_e64 v170, 1.0, v170, s[34:35]
	v_cndmask_b32_e64 v171, 1.0, v171, s[36:37]
	v_cndmask_b32_e64 v38, 1.0, v38, s[38:39]
	v_cndmask_b32_e64 v39, 1.0, v39, s[40:41]
	v_cndmask_b32_e64 v45, 0, v45, s[40:41]
	v_cndmask_b32_e32 v166, 0, v166, vcc
.Lsb_b_nomask:
	v_mul_f32_e32 v38, v38, v39
	v_mul_f32_e32 v32, v32, v33
	v_mul_f32_e32 v36, v36, v37
	v_mul_f32_e32 v180, v171, v38
	v_mul_f32_e32 v176, v155, v32
	v_mul_f32_e32 v179, v159, v36
	v_mul_f32_e32 v155, v170, v180
	v_mul_f32_e32 v34, v34, v35
	v_mul_f32_e32 v152, v158, v179
	v_mov_b32_e32 v182, v155
	v_mul_f32_e32 v178, v157, v34
	v_mov_b32_e32 v158, v152
	v_permlane32_swap_b32_e32 v155, v182
	v_mul_f32_e32 v177, v154, v176
	v_mul_f32_e32 v154, v156, v178
	v_permlane32_swap_b32_e32 v152, v158
	v_mul_f32_e32 v159, v155, v182
	v_mov_b32_e32 v156, v154
	v_pk_mul_f32 v[170:171], v[152:153], v[158:159]
	s_nop 0
	v_permlane32_swap_b32_e32 v154, v156
	v_mov_b32_e32 v155, v170
	v_mov_b32_e32 v157, v171
	v_mov_b32_e32 v181, v177
	v_pk_mul_f32 v[154:155], v[154:155], v[156:157]
	s_nop 0
	v_permlane32_swap_b32_e32 v177, v181
	v_mul_f32_e32 v152, v154, v155
	v_mul_f32_e32 v154, v152, v181
	v_mul_f32_e32 v156, v155, v156
	v_cndmask_b32_e64 v154, v152, v154, s[4:5]
	v_cndmask_b32_e64 v155, v155, v156, s[4:5]
	v_mul_f32_e32 v33, v33, v154
	v_mul_f32_e32 v32, v32, v154
	v_mul_f32_e32 v35, v35, v155
	v_mul_f32_e32 v34, v34, v155
	v_mul_f32_e32 v157, v169, v154
	v_mul_f32_e32 v33, v168, v33
	v_mul_f32_e32 v32, v167, v32
	v_mul_f32_e32 v154, v176, v154
	v_mul_f32_e32 v156, v165, v155
	v_mul_f32_e32 v35, v164, v35
	v_mul_f32_e32 v34, v163, v34
	v_mul_f32_e32 v155, v178, v155
	v_mul_f32_e32 v154, v166, v154
	v_mul_f32_e32 v155, v162, v155
	v_mul_f32_e32 v158, v171, v158
	v_cvt_pk_bf16_f32 v32, v154, v32
	v_cvt_pk_bf16_f32 v33, v33, v157
	v_cvt_pk_bf16_f32 v34, v155, v34
	v_cvt_pk_bf16_f32 v35, v35, v156
	v_cndmask_b32_e64 v158, v171, v158, s[4:5]
	s_waitcnt vmcnt(12)
	v_mfma_f32_32x32x16_bf16 v[16:31], v[32:35], v[112:115], v[16:31]
	v_mul_f32_e32 v36, v36, v158
	v_mul_f32_e32 v36, v43, v36
	v_mul_f32_e32 v43, v179, v158
	v_mul_f32_e32 v42, v42, v43
	v_mul_f32_e32 v43, v153, v182
	v_cndmask_b32_e64 v43, v153, v43, s[4:5]
	v_mul_f32_e32 v38, v38, v43
	v_mfma_f32_32x32x16_bf16 v[0:15], v[32:35], v[116:119], v[0:15]
	v_mul_f32_e32 v32, v180, v43
	v_mul_f32_e32 v37, v37, v158
	v_mul_f32_e32 v39, v39, v43
	v_mul_f32_e32 v34, v41, v38
	v_mul_f32_e32 v35, v40, v32
	v_mul_f32_e32 v47, v47, v158
	v_mul_f32_e32 v37, v46, v37
	v_mul_f32_e32 v45, v45, v43
	v_mul_f32_e32 v39, v44, v39
	v_cvt_pk_bf16_f32 v32, v42, v36
	v_cvt_pk_bf16_f32 v33, v37, v47
	v_cvt_pk_bf16_f32 v34, v35, v34
	v_cvt_pk_bf16_f32 v35, v39, v45
	v_mul_f32_e32 v36, v177, v181
	s_nop 0
	v_mfma_f32_32x32x16_bf16 v[16:31], v[32:35], v[120:123], v[16:31]
	v_mul_f32_e32 v153, v36, v152
	v_mfma_f32_32x32x16_bf16 v[0:15], v[32:35], v[124:127], v[0:15]
	v_lshl_add_u64 v[196:197], v[130:131], 0, s[98:99]
	global_load_dwordx4 v[112:115], v[196:197], off
	global_load_dwordx4 v[116:119], v[196:197], off offset:1024
	global_load_dwordx4 v[120:123], v[196:197], off offset:2048
	global_load_dwordx4 v[124:127], v[196:197], off offset:3072
	s_cmp_eq_u32 s90, 0
	s_cbranch_scc1 .LBB0_433
	s_mov_b32 s56, 0x800000
	v_cmp_gt_f32_e32 vcc, s56, v153
	s_cmp_eq_u64 vcc, exec
	s_cbranch_scc1 .LBB0_433
	s_add_i32 s90, s90, -1
	s_branch .Lsb_a
.LBB0_433:
	s_cmp_eq_u32 s42, 7
	s_cbranch_scc1 .LBB0_435
	s_add_i32 s91, s91, 8
	s_and_b32 s56, s91, 0x70
	s_and_b64 s[0:1], s[0:1], exec
	s_cselect_b32 s0, s86, s43
	s_or_b32 s0, s56, s0
	s_lshl_b32 s56, s0, 17
	v_lshl_add_u64 v[32:33], v[128:129], 0, s[56:57]
	s_lshl_b32 s56, s0, 12
	global_load_dwordx4 v[48:51], v[32:33], off offset:2048
	global_load_dwordx4 v[52:55], v[32:33], off offset:2080
	global_load_dwordx4 v[56:59], v[32:33], off offset:2112
	global_load_dwordx4 v[60:63], v[32:33], off offset:2144
	v_lshl_add_u64 v[32:33], v[132:133], 0, s[56:57]
	global_load_dwordx4 v[64:67], v[32:33], off
	global_load_dwordx4 v[68:71], v[32:33], off offset:1024
	global_load_dwordx4 v[72:75], v[32:33], off offset:2048
	global_load_dwordx4 v[80:83], v[32:33], off offset:3072
	v_lshl_add_u64 v[32:33], v[130:131], 0, s[56:57]
	global_load_dwordx4 v[76:79], v[32:33], off
	global_load_dwordx4 v[84:87], v[32:33], off offset:1024
	global_load_dwordx4 v[88:91], v[32:33], off offset:2048
	global_load_dwordx4 v[92:95], v[32:33], off offset:3072
	s_max_i32 s98, s0, 1
	s_add_i32 s98, s98, -1
	s_lshl_b32 s98, s98, 12
	v_lshl_add_u64 v[32:33], v[132:133], 0, s[98:99]
	global_load_dwordx4 v[96:99], v[32:33], off
	global_load_dwordx4 v[100:103], v[32:33], off offset:1024
	global_load_dwordx4 v[104:107], v[32:33], off offset:2048
	global_load_dwordx4 v[108:111], v[32:33], off offset:3072
	v_lshl_add_u64 v[32:33], v[130:131], 0, s[98:99]
	global_load_dwordx4 v[112:115], v[32:33], off
	global_load_dwordx4 v[116:119], v[32:33], off offset:1024
	global_load_dwordx4 v[120:123], v[32:33], off offset:2048
	global_load_dwordx4 v[124:127], v[32:33], off offset:3072

	.amdhsa_kernel _Z10hybrid_fwd4Args
		.amdhsa_group_segment_fixed_size 0
		.amdhsa_private_segment_fixed_size 0
		.amdhsa_kernarg_size 400
		.amdhsa_user_sgpr_count 2
		.amdhsa_user_sgpr_dispatch_ptr 0
		.amdhsa_user_sgpr_queue_ptr 0
		.amdhsa_user_sgpr_kernarg_segment_ptr 1
		.amdhsa_user_sgpr_dispatch_id 0
		.amdhsa_user_sgpr_kernarg_preload_length 0
		.amdhsa_user_sgpr_kernarg_preload_offset 0
		.amdhsa_user_sgpr_private_segment_size 0
		.amdhsa_uses_dynamic_stack 0
		.amdhsa_enable_private_segment 0
		.amdhsa_system_sgpr_workgroup_id_x 1
		.amdhsa_system_sgpr_workgroup_id_y 0
		.amdhsa_system_sgpr_workgroup_id_z 0
		.amdhsa_system_sgpr_workgroup_info 0
		.amdhsa_system_vgpr_workitem_id 2
		.amdhsa_next_free_vgpr 256
		.amdhsa_next_free_sgpr 100
		.amdhsa_accum_offset 256
		.amdhsa_reserve_vcc 1
		.amdhsa_float_round_mode_32 0
		.amdhsa_float_round_mode_16_64 0
		.amdhsa_float_denorm_mode_32 3
		.amdhsa_float_denorm_mode_16_64 3
		.amdhsa_dx10_clamp 1
		.amdhsa_ieee_mode 1
		.amdhsa_fp16_overflow 0
		.amdhsa_tg_split 0
		.amdhsa_exception_fp_ieee_invalid_op 0
		.amdhsa_exception_fp_denorm_src 0
		.amdhsa_exception_fp_ieee_div_zero 0
		.amdhsa_exception_fp_ieee_overflow 0
		.amdhsa_exception_fp_ieee_underflow 0
		.amdhsa_exception_fp_ieee_inexact 0
		.amdhsa_exception_int_div_zero 0
	.end_amdhsa_kernel

amdhsa.kernels:
  - .agpr_count:     0
    .args:
      - .offset:         0
        .size:           144
        .value_kind:     by_value
      - .offset:         144
        .size:           4
        .value_kind:     hidden_block_count_x
      - .offset:         148
        .size:           4
        .value_kind:     hidden_block_count_y
      - .offset:         152
        .size:           4
        .value_kind:     hidden_block_count_z
      - .offset:         156
        .size:           2
        .value_kind:     hidden_group_size_x
      - .offset:         158
        .size:           2
        .value_kind:     hidden_group_size_y
      - .offset:         160
        .size:           2
        .value_kind:     hidden_group_size_z
      - .offset:         162
        .size:           2
        .value_kind:     hidden_remainder_x
      - .offset:         164
        .size:           2
        .value_kind:     hidden_remainder_y
      - .offset:         166
        .size:           2
        .value_kind:     hidden_remainder_z
      - .offset:         184
        .size:           8
        .value_kind:     hidden_global_offset_x
      - .offset:         192
        .size:           8
        .value_kind:     hidden_global_offset_y
      - .offset:         200
        .size:           8
        .value_kind:     hidden_global_offset_z
      - .offset:         208
        .size:           2
        .value_kind:     hidden_grid_dims
      - .offset:         232
        .size:           8
        .value_kind:     hidden_multigrid_sync_arg
      - .offset:         264
        .size:           4
        .value_kind:     hidden_dynamic_lds_size
    .group_segment_fixed_size: 0
    .kernarg_segment_align: 8
    .kernarg_segment_size: 400
    .language:       OpenCL C
    .language_version:
      - 2
      - 0
    .max_flat_workgroup_size: 512
    .name:           _Z10hybrid_fwd4Args
    .private_segment_fixed_size: 0
    .sgpr_count:     106
    .sgpr_spill_count: 45
    .symbol:         _Z10hybrid_fwd4Args.kd
    .uniform_work_group_size: 1
    .uses_dynamic_stack: false
    .vgpr_count:     256
    .vgpr_spill_count: 0
    .wavefront_size: 64
